# GEMM phase prologues: K-tile 1 LDS-DMA loads issued before the first counted wait and barrier (vmcnt(4) -> vmcnt(10) after them), same barrier count
# baseline (speedup 1.0000x reference)
; #define PG8_STAGE(bufoff, gbase, voff) do { _Pragma("unroll") for (int _i = 0; _i < 2; ++_i) \
;     __builtin_amdgcn_global_load_lds((const unsigned*)((const char*)(gbase) + (voff)[_i]), (PG8_LAS unsigned*)(lds + (bufoff) + ldsw + _i * 8192), 16, 0, 0); } while (0)
; #define PG8_WAIT_V(n) asm volatile("s_waitcnt vmcnt(" #n ")" ::: "memory")
; #define PG8_BAR __builtin_amdgcn_s_barrier()
; template <class Epi>
; DI void gemm_phase(const bf16_t* __restrict__ gA, const bf16_t* __restrict__ gBt, int M, int N, int K, const Epi& E, char* lds_generic) {
;     ...
;   const char* cA = (const char*)gA + (size_t)cur.pm * tstep; const char* cB = (const char*)gBt + (size_t)cur.pn * tstep;
;   PG8_STAGE(PG8_SB(0, 0), cB, voffB); PG8_STAGE(PG8_SA(0, 0), cA, voffA); PG8_STAGE(PG8_SB(0, 1), cB + hstep, voffB); PG8_STAGE(PG8_SA(0, 1), cA + hstep, voffA);
;   if (wr == 1) PG8_BAR;
;   PG8_WAIT_V(4); PG8_BAR;
;   PG8_STAGE(PG8_SB(1, 0), cB + kstep, voffB); PG8_STAGE(PG8_SA(1, 0), cA + kstep, voffA); PG8_STAGE(PG8_SB(1, 1), cB + hstep + kstep, voffB);
;   PG8_WAIT_V(6); PG8_BAR;
.LBB0_131:
	v_readlane_b32 s28, v254, 58
	v_readlane_b32 s29, v254, 59
	v_mov_b32_e32 v139, v1
	v_readlane_b32 s30, v254, 54
	v_lshl_add_u64 v[10:11], s[28:29], 0, v[0:1]
	s_add_i32 s15, s5, 0x18000
	v_lshl_add_u64 v[12:13], s[28:29], 0, v[138:139]
	v_mov_b32_e32 v135, v1
	v_readlane_b32 s31, v254, 55
	v_lshl_add_u64 v[10:11], v[10:11], 0, s[10:11]
	s_mov_b32 m0, s15
	s_add_i32 s16, s5, 0x1a000
	v_lshl_add_u64 v[14:15], s[30:31], 0, v[134:135]
	v_mov_b32_e32 v137, v1
	global_load_lds_dwordx4 v[10:11], off
	v_lshl_add_u64 v[10:11], v[12:13], 0, s[10:11]
	s_mov_b32 m0, s16
	s_add_i32 s18, s5, 0x8000
	v_lshl_add_u64 v[16:17], s[30:31], 0, v[136:137]
	global_load_lds_dwordx4 v[10:11], off
	v_lshl_add_u64 v[10:11], v[14:15], 0, s[10:11]
	s_mov_b32 m0, s18
	s_add_i32 s19, s5, 0xa000
	v_readlane_b32 s22, v254, 60
	global_load_lds_dwordx4 v[10:11], off
	v_lshl_add_u64 v[10:11], v[16:17], 0, s[10:11]
	s_mov_b32 m0, s19
	s_add_i32 s20, s5, 0x1c000
	v_readlane_b32 s23, v254, 61
	global_load_lds_dwordx4 v[10:11], off
	s_nop 0
	v_lshl_add_u64 v[10:11], s[22:23], 0, v[0:1]
	s_mov_b32 m0, s20
	s_add_i32 s21, s5, 0x1e000
	global_load_lds_dwordx4 v[10:11], off
	v_lshl_add_u64 v[10:11], s[22:23], 0, v[138:139]
	s_mov_b32 m0, s21
	s_lshl_b32 s0, s0, 5
	global_load_lds_dwordx4 v[10:11], off
	s_waitcnt vmcnt(10)
	s_barrier
	v_and_b32_e32 v10, 15, v2
	v_lshrrev_b32_e32 v2, 1, v2
	v_and_b32_e32 v11, 24, v2
	v_lshlrev_b32_e32 v2, 1, v11
	v_lshl_or_b32 v153, s1, 6, v10
	v_lshl_or_b32 v2, v10, 6, v2
	v_lshlrev_b32_e32 v10, 2, v10
	s_lshl_b32 s22, s1, 13
	v_and_b32_e32 v12, 32, v10
	s_and_b32 s0, s0, 0x60
	v_lshlrev_b32_e32 v3, 3, v3
	v_bitop3_b32 v154, v2, s22, v12 bitop3:0xde
	s_lshl_b32 s22, s0, 7
	v_bitop3_b32 v12, v2, s22, v12 bitop3:0xde
	v_lshlrev_b32_e32 v2, 1, v3
	v_mov_b32_e32 v3, v1
	v_lshl_add_u64 v[140:141], s[70:71], 0, v[2:3]
	v_lshlrev_b32_e32 v2, 14, v4
	v_and_b32_e32 v2, 0xffff8000, v2
	v_lshl_add_u32 v2, v5, 11, v2
	v_and_b32_e32 v3, 1, v4
	v_lshl_or_b32 v2, v3, 6, v2
	v_lshl_add_u32 v142, v6, 1, v2
	v_lshlrev_b32_e32 v2, 14, v7
	s_lshl_b32 s1, s1, 8
	v_and_b32_e32 v2, 0xffff8000, v2
	s_waitcnt vmcnt(6)
	s_add_i32 s1, s1, 0x20040
	v_lshl_add_u32 v2, v8, 11, v2
	v_and_b32_e32 v3, 1, v7
	v_or_b32_e32 v155, s1, v10
	v_or_b32_e32 v156, s0, v11
	v_lshl_or_b32 v2, v3, 6, v2
	v_readlane_b32 s0, v254, 50
	v_mov_b32_e32 v143, v1
	v_lshl_add_u32 v144, v9, 1, v2
	v_mov_b32_e32 v145, v1
	s_mov_b32 s53, 0
	v_or_b32_e32 v157, 0x10000, v12
	v_add_u32_e32 v158, 0x10400, v12
	v_add_u32_e32 v159, 0x10800, v12
	v_add_u32_e32 v160, 0x10c00, v12
	s_add_i32 s33, s5, 0xc000
	s_add_i32 s35, s5, 0xe000
	v_or_b32_e32 v161, 0x14000, v12
	v_add_u32_e32 v163, 0x14400, v12
	v_add_u32_e32 v165, 0x14800, v12
	v_add_u32_e32 v166, 0x14c00, v12
	v_or_b32_e32 v167, 0x18000, v12
	v_add_u32_e32 v168, 0x18400, v12
	v_add_u32_e32 v169, 0x18800, v12
	v_add_u32_e32 v170, 0x18c00, v12
	v_or_b32_e32 v171, 0x1c000, v12
	v_add_u32_e32 v172, 0x1c400, v12
	v_add_u32_e32 v173, 0x1c800, v12
	v_add_u32_e32 v174, 0x1cc00, v12
	v_readlane_b32 s58, v255, 31
	s_mov_b32 s59, s0
	s_barrier
	v_readlane_b32 s1, v254, 51
	s_branch .LBB0_134

; #define PG8_STAGE(bufoff, gbase, voff) do { _Pragma("unroll") for (int _i = 0; _i < 2; ++_i) \
;     __builtin_amdgcn_global_load_lds((const unsigned*)((const char*)(gbase) + (voff)[_i]), (PG8_LAS unsigned*)(lds + (bufoff) + ldsw + _i * 8192), 16, 0, 0); } while (0)
; #define PG8_WAIT_V(n) asm volatile("s_waitcnt vmcnt(" #n ")" ::: "memory")
; #define PG8_BAR __builtin_amdgcn_s_barrier()
; template <class Epi>
; DI void gemm_phase(const bf16_t* __restrict__ gA, const bf16_t* __restrict__ gBt, int M, int N, int K, const Epi& E, char* lds_generic) {
;     ...
;   const char* cA = (const char*)gA + (size_t)cur.pm * tstep; const char* cB = (const char*)gBt + (size_t)cur.pn * tstep;
;   PG8_STAGE(PG8_SB(0, 0), cB, voffB); PG8_STAGE(PG8_SA(0, 0), cA, voffA); PG8_STAGE(PG8_SB(0, 1), cB + hstep, voffB); PG8_STAGE(PG8_SA(0, 1), cA + hstep, voffA);
;   if (wr == 1) PG8_BAR;
;   PG8_WAIT_V(4); PG8_BAR;
;   PG8_STAGE(PG8_SB(1, 0), cB + kstep, voffB); PG8_STAGE(PG8_SA(1, 0), cA + kstep, voffA); PG8_STAGE(PG8_SB(1, 1), cB + hstep + kstep, voffB);
;   PG8_WAIT_V(6); PG8_BAR;
.LBB0_153:
	v_and_b32_e32 v18, 15, v2
	v_lshrrev_b32_e32 v2, 1, v2
	v_and_b32_e32 v2, 24, v2
	v_lshlrev_b32_e32 v19, 1, v2
	v_lshl_or_b32 v153, s0, 6, v18
	v_lshl_or_b32 v19, v18, 6, v19
	v_lshlrev_b32_e32 v18, 2, v18
	s_lshl_b32 s1, s1, 5
	v_readlane_b32 s28, v255, 9
	s_lshl_b32 s15, s0, 13
	v_and_b32_e32 v20, 32, v18
	s_and_b32 s1, s1, 0x60
	v_readlane_b32 s29, v255, 10
	v_bitop3_b32 v154, v19, s15, v20 bitop3:0xde
	s_lshl_b32 s15, s1, 7
	v_lshl_add_u64 v[10:11], s[28:29], 0, v[0:1]
	v_mov_b32_e32 v139, v1
	v_readlane_b32 s30, v255, 5
	v_bitop3_b32 v155, v19, s15, v20 bitop3:0xde
	s_add_i32 s15, s5, 0x18000
	v_lshl_add_u64 v[12:13], s[28:29], 0, v[138:139]
	v_mov_b32_e32 v135, v1
	v_readlane_b32 s31, v255, 6
	v_lshl_add_u64 v[10:11], v[10:11], 0, s[10:11]
	s_mov_b32 m0, s15
	s_add_i32 s16, s5, 0x1a000
	v_lshl_add_u64 v[14:15], s[30:31], 0, v[134:135]
	v_mov_b32_e32 v137, v1
	global_load_lds_dwordx4 v[10:11], off
	v_lshl_add_u64 v[10:11], v[12:13], 0, s[10:11]
	s_mov_b32 m0, s16
	s_add_i32 s18, s5, 0x8000
	v_lshl_add_u64 v[16:17], s[30:31], 0, v[136:137]
	global_load_lds_dwordx4 v[10:11], off
	v_lshl_add_u64 v[10:11], v[14:15], 0, s[10:11]
	s_mov_b32 m0, s18
	s_add_i32 s19, s5, 0xa000
	v_readlane_b32 s22, v255, 11
	global_load_lds_dwordx4 v[10:11], off
	v_lshl_add_u64 v[10:11], v[16:17], 0, s[10:11]
	s_mov_b32 m0, s19
	s_add_i32 s20, s5, 0x1c000
	v_readlane_b32 s23, v255, 12
	global_load_lds_dwordx4 v[10:11], off
	s_nop 0
	v_lshl_add_u64 v[10:11], s[22:23], 0, v[0:1]
	s_mov_b32 m0, s20
	s_add_i32 s21, s5, 0x1e000
	global_load_lds_dwordx4 v[10:11], off
	v_lshl_add_u64 v[10:11], s[22:23], 0, v[138:139]
	s_mov_b32 m0, s21
	v_or_b32_e32 v157, s1, v2
	global_load_lds_dwordx4 v[10:11], off
	s_waitcnt vmcnt(10)
	s_barrier
	v_lshlrev_b32_e32 v2, 14, v3
	v_and_b32_e32 v2, 0xffff8000, v2
	v_lshl_add_u32 v2, v4, 11, v2
	v_and_b32_e32 v3, 1, v3
	v_lshl_or_b32 v2, v3, 6, v2
	v_lshl_add_u32 v142, v5, 1, v2
	v_lshlrev_b32_e32 v2, 14, v7
	s_lshl_b32 s0, s0, 8
	v_and_b32_e32 v2, 0xffff8000, v2
	v_lshlrev_b32_e32 v6, 3, v6
	s_waitcnt vmcnt(6)
	s_add_i32 s0, s0, 0x20040
	v_lshl_add_u32 v2, v8, 11, v2
	v_and_b32_e32 v3, 1, v7
	v_or_b32_e32 v156, s0, v18
	v_lshlrev_b32_e32 v10, 1, v6
	v_mov_b32_e32 v11, v1
	v_lshl_or_b32 v2, v3, 6, v2
	v_readlane_b32 s0, v254, 63
	v_lshl_add_u64 v[140:141], s[70:71], 0, v[10:11]
	v_mov_b32_e32 v143, v1
	v_lshl_add_u32 v144, v9, 1, v2
	v_mov_b32_e32 v145, v1
	s_mov_b32 s42, 0
	v_readlane_b32 s35, v255, 32
	s_mov_b32 s53, s0
	s_barrier
	v_readlane_b32 s1, v255, 0
	s_branch .LBB0_156

; DI float bflo(unsigned u) { return __uint_as_float(u << 16); }
; DI float bfhi(unsigned u) { return __uint_as_float(u & 0xffff0000u); }
;   DI void init(f32x4 (&acc)[2][2][4][2], const Unit&, int, int, int, int) const { acc_zero(acc); }
;   DI void init(f32x4 (&acc)[2][2][4][2], const Unit&, int, int, int, int) const { acc_zero(acc); }
; #define PG8_STAGE(bufoff, gbase, voff) do { _Pragma("unroll") for (int _i = 0; _i < 2; ++_i) \
;     __builtin_amdgcn_global_load_lds((const unsigned*)((const char*)(gbase) + (voff)[_i]), (PG8_LAS unsigned*)(lds + (bufoff) + ldsw + _i * 8192), 16, 0, 0); } while (0)
; #define PG8_WAIT_V(n) asm volatile("s_waitcnt vmcnt(" #n ")" ::: "memory")
; #define PG8_BAR __builtin_amdgcn_s_barrier()
;   DI void init(f32x4 (&acc)[2][2][4][2], const Unit& u, int wr, int wc, int fr, int fq) const {
;     const int row0 = u.pm * BM + wr * 64 + fr, col0 = u.pn * BM + wc * 32 + 8 * fq; const float ic = 1.f / coef;
; #pragma unroll
;     for (int ai = 0; ai < 2; ++ai)
; #pragma unroll
;       for (int m = 0; m < 4; ++m) { const bf16_t* rowp = src + (size_t)(row0 + ai * HALF + m * 16) * DM + col0;
; #pragma unroll
;         for (int bj = 0; bj < 2; ++bj) { const u32x4 w = *(const u32x4*)(rowp + bj * HALF);
;           acc[ai][bj][m][0] = (f32x4){bflo(w.x), bfhi(w.x), bflo(w.y), bfhi(w.y)} * ic; acc[ai][bj][m][1] = (f32x4){bflo(w.z), bfhi(w.z), bflo(w.w), bfhi(w.w)} * ic; } }
; template <class Epi>
; DI void gemm_phase(const bf16_t* __restrict__ gA, const bf16_t* __restrict__ gBt, int M, int N, int K, const Epi& E, char* lds_generic) {
;     ...
;   const char* cA = (const char*)gA + (size_t)cur.pm * tstep; const char* cB = (const char*)gBt + (size_t)cur.pn * tstep;
;   PG8_STAGE(PG8_SB(0, 0), cB, voffB); PG8_STAGE(PG8_SA(0, 0), cA, voffA); PG8_STAGE(PG8_SB(0, 1), cB + hstep, voffB); PG8_STAGE(PG8_SA(0, 1), cA + hstep, voffA);
;   if (wr == 1) PG8_BAR;
;   PG8_WAIT_V(4); PG8_BAR;
;   PG8_STAGE(PG8_SB(1, 0), cB + kstep, voffB); PG8_STAGE(PG8_SA(1, 0), cA + kstep, voffA); PG8_STAGE(PG8_SB(1, 1), cB + hstep + kstep, voffB);
;   PG8_WAIT_V(6); PG8_BAR;
.LBB0_502:
	v_readlane_b32 s22, v254, 45
	v_readlane_b32 s23, v254, 46
	s_waitcnt vmcnt(0)
	v_lshlrev_b32_e32 v102, 16, v42
	v_and_b32_e32 v103, 0xffff0000, v42
	v_lshlrev_b32_e32 v104, 16, v43
	v_and_b32_e32 v105, 0xffff0000, v43
	v_lshlrev_b32_e32 v114, 16, v44
	v_and_b32_e32 v115, 0xffff0000, v44
	v_lshlrev_b32_e32 v116, 16, v45
	v_and_b32_e32 v117, 0xffff0000, v45
	v_lshlrev_b32_e32 v86, 16, v22
	v_and_b32_e32 v87, 0xffff0000, v22
	v_lshlrev_b32_e32 v88, 16, v23
	v_and_b32_e32 v89, 0xffff0000, v23
	v_lshlrev_b32_e32 v98, 16, v24
	v_and_b32_e32 v99, 0xffff0000, v24
	v_lshlrev_b32_e32 v100, 16, v25
	v_and_b32_e32 v101, 0xffff0000, v25
	v_lshlrev_b32_e32 v42, 16, v38
	v_and_b32_e32 v43, 0xffff0000, v38
	v_lshlrev_b32_e32 v44, 16, v39
	v_and_b32_e32 v45, 0xffff0000, v39
	v_lshlrev_b32_e32 v22, 16, v40
	v_and_b32_e32 v23, 0xffff0000, v40
	v_lshlrev_b32_e32 v24, 16, v41
	v_and_b32_e32 v25, 0xffff0000, v41
	v_lshlrev_b32_e32 v38, 16, v46
	v_and_b32_e32 v39, 0xffff0000, v46
	v_lshlrev_b32_e32 v40, 16, v47
	v_and_b32_e32 v41, 0xffff0000, v47
	v_lshl_add_u64 v[46:47], s[22:23], 0, v[0:1]
	v_mov_b32_e32 v131, v1
	v_readlane_b32 s28, v254, 41
	s_add_i32 s8, s6, 0x18000
	v_lshlrev_b32_e32 v90, 16, v58
	v_and_b32_e32 v91, 0xffff0000, v58
	v_lshlrev_b32_e32 v92, 16, v59
	v_and_b32_e32 v93, 0xffff0000, v59
	v_lshlrev_b32_e32 v82, 16, v60
	v_and_b32_e32 v83, 0xffff0000, v60
	v_lshlrev_b32_e32 v84, 16, v61
	v_and_b32_e32 v85, 0xffff0000, v61
	v_lshlrev_b32_e32 v58, 16, v18
	v_and_b32_e32 v59, 0xffff0000, v18
	v_lshlrev_b32_e32 v60, 16, v19
	v_and_b32_e32 v61, 0xffff0000, v19
	v_lshlrev_b32_e32 v74, 16, v20
	v_and_b32_e32 v75, 0xffff0000, v20
	v_lshlrev_b32_e32 v76, 16, v21
	v_and_b32_e32 v77, 0xffff0000, v21
	v_lshlrev_b32_e32 v18, 16, v48
	v_and_b32_e32 v19, 0xffff0000, v48
	v_lshlrev_b32_e32 v20, 16, v49
	v_and_b32_e32 v21, 0xffff0000, v49
	v_lshl_add_u64 v[48:49], s[22:23], 0, v[130:131]
	v_mov_b32_e32 v135, v1
	v_readlane_b32 s29, v254, 42
	v_lshl_add_u64 v[46:47], v[46:47], 0, s[10:11]
	s_mov_b32 m0, s8
	s_add_i32 s9, s6, 0x1a000
	v_lshl_add_u64 v[70:71], s[28:29], 0, v[134:135]
	v_mov_b32_e32 v133, v1
	global_load_lds_dwordx4 v[46:47], off
	v_lshl_add_u64 v[46:47], v[48:49], 0, s[10:11]
	s_mov_b32 m0, s9
	s_add_i32 s19, s6, 0x8000
	v_lshl_add_u64 v[72:73], s[28:29], 0, v[132:133]
	global_load_lds_dwordx4 v[46:47], off
	v_lshl_add_u64 v[46:47], v[70:71], 0, s[10:11]
	s_mov_b32 m0, s19
	s_add_i32 s33, s6, 0xa000
	v_readlane_b32 s24, v254, 47
	global_load_lds_dwordx4 v[46:47], off
	v_lshl_add_u64 v[46:47], v[72:73], 0, s[10:11]
	s_mov_b32 m0, s33
	s_add_i32 s35, s6, 0x1c000
	v_readlane_b32 s25, v254, 48
	global_load_lds_dwordx4 v[46:47], off
	s_nop 0
	v_lshl_add_u64 v[46:47], s[24:25], 0, v[0:1]
	s_mov_b32 m0, s35
	s_add_i32 s42, s6, 0x1e000
	global_load_lds_dwordx4 v[46:47], off
	v_lshl_add_u64 v[46:47], s[24:25], 0, v[130:131]
	s_mov_b32 m0, s42
	v_or_b32_e32 v144, s20, v140
	global_load_lds_dwordx4 v[46:47], off
	s_waitcnt vmcnt(10)
	s_barrier
	v_lshlrev_b32_e32 v145, 6, v144
	v_lshlrev_b32_e32 v146, 4, v136
	s_movk_i32 s20, 0x3c0
	v_lshlrev_b32_e32 v147, 2, v144
	v_and_or_b32 v145, v145, s20, v146
	s_lshl_b32 s1, s1, 13
	v_and_b32_e32 v147, 32, v147
	v_lshl_or_b32 v146, v140, 6, v146
	v_lshlrev_b32_e32 v140, 2, v140
	v_bitop3_b32 v145, v145, s1, v147 bitop3:0xde
	s_lshl_b32 s1, s5, 12
	v_and_b32_e32 v140, 32, v140
	v_bitop3_b32 v146, v146, s1, v140 bitop3:0xde
	v_cmp_eq_u32_e64 s[36:37], 0, v136
	v_lshlrev_b32_e32 v136, 14, v143
	v_lshlrev_b32_e32 v140, 14, v138
	v_and_b32_e32 v136, 0xffff8000, v136
	v_and_b32_e32 v140, 0xffff8000, v140
	s_waitcnt vmcnt(6)
	v_or_b32_e32 v147, s0, v137
	v_lshl_add_u32 v136, v142, 11, v136
	v_and_b32_e32 v137, 1, v143
	v_lshl_add_u32 v139, v139, 11, v140
	v_and_b32_e32 v138, 1, v138
	v_readlane_b32 s0, v254, 35
	v_lshl_or_b32 v136, v137, 6, v136
	v_lshl_or_b32 v138, v138, 6, v139
	v_readlane_b32 s1, v254, 36
	v_lshlrev_b32_e32 v118, 16, v62
	v_and_b32_e32 v119, 0xffff0000, v62
	v_lshlrev_b32_e32 v120, 16, v63
	v_and_b32_e32 v121, 0xffff0000, v63
	v_lshlrev_b32_e32 v110, 16, v64
	v_and_b32_e32 v111, 0xffff0000, v64
	v_lshlrev_b32_e32 v112, 16, v65
	v_and_b32_e32 v113, 0xffff0000, v65
	v_lshlrev_b32_e32 v122, 16, v54
	v_and_b32_e32 v123, 0xffff0000, v54
	v_lshlrev_b32_e32 v124, 16, v55
	v_and_b32_e32 v125, 0xffff0000, v55
	v_lshlrev_b32_e32 v126, 16, v56
	v_and_b32_e32 v127, 0xffff0000, v56
	v_lshlrev_b32_e32 v128, 16, v57
	v_and_b32_e32 v129, 0xffff0000, v57
	v_lshlrev_b32_e32 v62, 16, v50
	v_and_b32_e32 v63, 0xffff0000, v50
	v_lshlrev_b32_e32 v64, 16, v51
	v_and_b32_e32 v65, 0xffff0000, v51
	v_lshlrev_b32_e32 v50, 16, v52
	v_and_b32_e32 v51, 0xffff0000, v52
	v_lshlrev_b32_e32 v52, 16, v53
	v_and_b32_e32 v53, 0xffff0000, v53
	v_lshlrev_b32_e32 v54, 16, v10
	v_and_b32_e32 v55, 0xffff0000, v10
	v_lshlrev_b32_e32 v56, 16, v11
	v_and_b32_e32 v57, 0xffff0000, v11
	v_lshlrev_b32_e32 v66, 16, v12
	v_and_b32_e32 v67, 0xffff0000, v12
	v_lshlrev_b32_e32 v68, 16, v13
	v_and_b32_e32 v69, 0xffff0000, v13
	v_lshlrev_b32_e32 v10, 16, v2
	v_and_b32_e32 v11, 0xffff0000, v2
	v_lshlrev_b32_e32 v12, 16, v3
	v_and_b32_e32 v13, 0xffff0000, v3
	v_lshlrev_b32_e32 v2, 16, v4
	v_and_b32_e32 v3, 0xffff0000, v4
	v_lshlrev_b32_e32 v4, 16, v5
	v_and_b32_e32 v5, 0xffff0000, v5
	v_lshlrev_b32_e32 v94, 16, v14
	v_and_b32_e32 v95, 0xffff0000, v14
	v_lshlrev_b32_e32 v96, 16, v15
	v_and_b32_e32 v97, 0xffff0000, v15
	v_lshlrev_b32_e32 v106, 16, v16
	v_and_b32_e32 v107, 0xffff0000, v16
	v_lshlrev_b32_e32 v108, 16, v17
	v_and_b32_e32 v109, 0xffff0000, v17
	v_lshlrev_b32_e32 v46, 16, v30
	v_and_b32_e32 v47, 0xffff0000, v30
	v_lshlrev_b32_e32 v48, 16, v31
	v_and_b32_e32 v49, 0xffff0000, v31
	v_lshlrev_b32_e32 v30, 16, v32
	v_and_b32_e32 v31, 0xffff0000, v32
	v_lshlrev_b32_e32 v32, 16, v33
	v_and_b32_e32 v33, 0xffff0000, v33
	v_lshlrev_b32_e32 v70, 16, v6
	v_and_b32_e32 v71, 0xffff0000, v6
	v_lshlrev_b32_e32 v72, 16, v7
	v_and_b32_e32 v73, 0xffff0000, v7
	v_lshlrev_b32_e32 v78, 16, v8
	v_and_b32_e32 v79, 0xffff0000, v8
	v_lshlrev_b32_e32 v80, 16, v9
	v_and_b32_e32 v81, 0xffff0000, v9
	v_lshlrev_b32_e32 v14, 16, v26
	v_and_b32_e32 v15, 0xffff0000, v26
	v_lshlrev_b32_e32 v16, 16, v27
	v_and_b32_e32 v17, 0xffff0000, v27
	v_lshlrev_b32_e32 v6, 16, v28
	v_and_b32_e32 v7, 0xffff0000, v28
	v_lshlrev_b32_e32 v8, 16, v29
	v_and_b32_e32 v9, 0xffff0000, v29
	v_lshlrev_b32_e32 v26, 16, v34
	v_and_b32_e32 v27, 0xffff0000, v34
	v_lshlrev_b32_e32 v28, 16, v35
	v_and_b32_e32 v29, 0xffff0000, v35
	v_lshlrev_b32_e32 v34, 16, v36
	v_and_b32_e32 v35, 0xffff0000, v36
	v_lshlrev_b32_e32 v36, 16, v37
	v_and_b32_e32 v37, 0xffff0000, v37
	s_mov_b32 s53, 0
	v_lshl_add_u32 v136, v148, 1, v136
	v_mov_b32_e32 v137, v1
	v_lshl_add_u32 v138, v141, 1, v138
	v_mov_b32_e32 v139, v1
	v_readlane_b32 s20, v254, 33
	s_mov_b32 s21, s0
	s_mov_b64 s[0:1], s[22:23]
	s_barrier
	s_branch .LBB0_504

; #define PG8_STAGE(bufoff, gbase, voff) do { _Pragma("unroll") for (int _i = 0; _i < 2; ++_i) \
;     __builtin_amdgcn_global_load_lds((const unsigned*)((const char*)(gbase) + (voff)[_i]), (PG8_LAS unsigned*)(lds + (bufoff) + ldsw + _i * 8192), 16, 0, 0); } while (0)
; #define PG8_WAIT_V(n) asm volatile("s_waitcnt vmcnt(" #n ")" ::: "memory")
; #define PG8_BAR __builtin_amdgcn_s_barrier()
; template <class Epi>
; DI void gemm_phase(const bf16_t* __restrict__ gA, const bf16_t* __restrict__ gBt, int M, int N, int K, const Epi& E, char* lds_generic) {
;     ...
;   const char* cA = (const char*)gA + (size_t)cur.pm * tstep; const char* cB = (const char*)gBt + (size_t)cur.pn * tstep;
;   PG8_STAGE(PG8_SB(0, 0), cB, voffB); PG8_STAGE(PG8_SA(0, 0), cA, voffA); PG8_STAGE(PG8_SB(0, 1), cB + hstep, voffB); PG8_STAGE(PG8_SA(0, 1), cA + hstep, voffA);
;   if (wr == 1) PG8_BAR;
;   PG8_WAIT_V(4); PG8_BAR;
;   PG8_STAGE(PG8_SB(1, 0), cB + kstep, voffB); PG8_STAGE(PG8_SA(1, 0), cA + kstep, voffA); PG8_STAGE(PG8_SB(1, 1), cB + hstep + kstep, voffB);
;   PG8_WAIT_V(6); PG8_BAR;
.LBB0_595:
	v_and_b32_e32 v18, 15, v2
	v_lshrrev_b32_e32 v2, 1, v2
	v_and_b32_e32 v2, 24, v2
	v_lshl_add_u64 v[10:11], s[40:41], 0, v[0:1]
	v_mov_b32_e32 v139, v1
	v_lshlrev_b32_e32 v19, 1, v2
	s_add_i32 s13, s72, 0x18000
	v_lshl_add_u64 v[12:13], s[40:41], 0, v[138:139]
	v_mov_b32_e32 v135, v1
	v_lshl_or_b32 v153, s8, 6, v18
	v_lshl_or_b32 v19, v18, 6, v19
	v_lshlrev_b32_e32 v18, 2, v18
	v_lshl_add_u64 v[10:11], v[10:11], 0, s[10:11]
	s_mov_b32 m0, s13
	s_add_i32 s35, s72, 0x1a000
	v_lshl_add_u64 v[14:15], s[28:29], 0, v[134:135]
	v_mov_b32_e32 v137, v1
	s_lshl_b32 s9, s8, 13
	v_and_b32_e32 v20, 32, v18
	s_lshl_b32 s6, s6, 5
	global_load_lds_dwordx4 v[10:11], off
	v_lshl_add_u64 v[10:11], v[12:13], 0, s[10:11]
	s_mov_b32 m0, s35
	s_add_i32 s53, s72, 0x8000
	v_lshl_add_u64 v[16:17], s[28:29], 0, v[136:137]
	v_bitop3_b32 v154, v19, s9, v20 bitop3:0xde
	s_and_b32 s9, s6, 0x60
	global_load_lds_dwordx4 v[10:11], off
	v_lshl_add_u64 v[10:11], v[14:15], 0, s[10:11]
	s_mov_b32 m0, s53
	s_add_i32 s74, s72, 0xa000
	s_lshl_b32 s6, s9, 7
	global_load_lds_dwordx4 v[10:11], off
	v_lshl_add_u64 v[10:11], v[16:17], 0, s[10:11]
	s_mov_b32 m0, s74
	s_add_i32 s60, s72, 0x1c000
	v_bitop3_b32 v155, v19, s6, v20 bitop3:0xde
	global_load_lds_dwordx4 v[10:11], off
	v_lshl_add_u64 v[10:11], s[80:81], 0, v[0:1]
	s_mov_b32 m0, s60
	s_add_i32 s6, s72, 0x1e000
	global_load_lds_dwordx4 v[10:11], off
	v_lshl_add_u64 v[10:11], s[80:81], 0, v[138:139]
	s_mov_b32 m0, s6
	v_or_b32_e32 v157, s9, v2
	global_load_lds_dwordx4 v[10:11], off
	s_waitcnt vmcnt(10)
	s_barrier
	v_lshlrev_b32_e32 v2, 14, v3
	v_and_b32_e32 v2, 0xffff8000, v2
	v_lshl_add_u32 v2, v5, 11, v2
	v_and_b32_e32 v3, 1, v3
	v_lshl_or_b32 v2, v3, 6, v2
	v_lshl_add_u32 v142, v6, 1, v2
	v_lshlrev_b32_e32 v2, 14, v7
	v_and_b32_e32 v2, 0xffff8000, v2
	v_lshlrev_b32_e32 v4, 3, v4
	s_waitcnt vmcnt(6)
	s_lshl_b32 s8, s8, 8
	v_lshl_add_u32 v2, v8, 11, v2
	v_and_b32_e32 v3, 1, v7
	v_readlane_b32 s18, v255, 27
	v_lshlrev_b32_e32 v10, 1, v4
	v_mov_b32_e32 v11, v1
	s_add_i32 s8, s8, 0x20040
	v_lshl_or_b32 v2, v3, 6, v2
	v_readlane_b32 s19, v255, 28
	v_lshl_add_u64 v[140:141], s[84:85], 0, v[10:11]
	v_or_b32_e32 v156, s8, v18
	v_mov_b32_e32 v143, v1
	v_lshl_add_u32 v144, v9, 1, v2
	v_mov_b32_e32 v145, v1
	s_mov_b32 s8, 0
	v_readlane_b32 s9, v255, 33
	s_mov_b32 s19, s18
	s_mov_b64 s[30:31], s[40:41]
	s_barrier
	s_branch .LBB0_598

; DI float bflo(unsigned u) { return __uint_as_float(u << 16); }
; DI float bfhi(unsigned u) { return __uint_as_float(u & 0xffff0000u); }
;   DI void init(f32x4 (&acc)[2][2][4][2], const Unit&, int, int, int, int) const { acc_zero(acc); }
;   DI void init(f32x4 (&acc)[2][2][4][2], const Unit&, int, int, int, int) const { acc_zero(acc); }
; #define PG8_STAGE(bufoff, gbase, voff) do { _Pragma("unroll") for (int _i = 0; _i < 2; ++_i) \
;     __builtin_amdgcn_global_load_lds((const unsigned*)((const char*)(gbase) + (voff)[_i]), (PG8_LAS unsigned*)(lds + (bufoff) + ldsw + _i * 8192), 16, 0, 0); } while (0)
; #define PG8_WAIT_V(n) asm volatile("s_waitcnt vmcnt(" #n ")" ::: "memory")
; #define PG8_BAR __builtin_amdgcn_s_barrier()
;   DI void init(f32x4 (&acc)[2][2][4][2], const Unit& u, int wr, int wc, int fr, int fq) const {
;     const int row0 = u.pm * BM + wr * 64 + fr, col0 = u.pn * BM + wc * 32 + 8 * fq; const float ic = 1.f / coef;
; #pragma unroll
;     for (int ai = 0; ai < 2; ++ai)
; #pragma unroll
;       for (int m = 0; m < 4; ++m) { const bf16_t* rowp = src + (size_t)(row0 + ai * HALF + m * 16) * DM + col0;
; #pragma unroll
;         for (int bj = 0; bj < 2; ++bj) { const u32x4 w = *(const u32x4*)(rowp + bj * HALF);
;           acc[ai][bj][m][0] = (f32x4){bflo(w.x), bfhi(w.x), bflo(w.y), bfhi(w.y)} * ic; acc[ai][bj][m][1] = (f32x4){bflo(w.z), bfhi(w.z), bflo(w.w), bfhi(w.w)} * ic; } }
; template <class Epi>
; DI void gemm_phase(const bf16_t* __restrict__ gA, const bf16_t* __restrict__ gBt, int M, int N, int K, const Epi& E, char* lds_generic) {
;     ...
;   const char* cA = (const char*)gA + (size_t)cur.pm * tstep; const char* cB = (const char*)gBt + (size_t)cur.pn * tstep;
;   PG8_STAGE(PG8_SB(0, 0), cB, voffB); PG8_STAGE(PG8_SA(0, 0), cA, voffA); PG8_STAGE(PG8_SB(0, 1), cB + hstep, voffB); PG8_STAGE(PG8_SA(0, 1), cA + hstep, voffA);
;   if (wr == 1) PG8_BAR;
;   PG8_WAIT_V(4); PG8_BAR;
;   PG8_STAGE(PG8_SB(1, 0), cB + kstep, voffB); PG8_STAGE(PG8_SA(1, 0), cA + kstep, voffA); PG8_STAGE(PG8_SB(1, 1), cB + hstep + kstep, voffB);
;   PG8_WAIT_V(6); PG8_BAR;
.LBB0_671:
	s_lshl_b64 s[20:21], s[26:27], 1
	v_readlane_b32 s19, v255, 58
	s_add_u32 s26, s19, s20
	v_readlane_b32 s19, v255, 56
	s_waitcnt vmcnt(0)
	v_lshlrev_b32_e32 v118, 16, v54
	v_and_b32_e32 v119, 0xffff0000, v54
	v_lshlrev_b32_e32 v120, 16, v55
	v_and_b32_e32 v121, 0xffff0000, v55
	v_lshlrev_b32_e32 v114, 16, v56
	v_and_b32_e32 v115, 0xffff0000, v56
	v_lshlrev_b32_e32 v116, 16, v57
	v_and_b32_e32 v117, 0xffff0000, v57
	v_lshlrev_b32_e32 v54, 16, v26
	v_and_b32_e32 v55, 0xffff0000, v26
	v_lshlrev_b32_e32 v56, 16, v27
	v_and_b32_e32 v57, 0xffff0000, v27
	v_lshl_add_u64 v[26:27], s[90:91], 0, v[0:1]
	v_mov_b32_e32 v135, v1
	s_addc_u32 s27, s19, s21
	s_add_i32 s59, s12, 0x18000
	v_lshlrev_b32_e32 v94, 16, v50
	v_and_b32_e32 v95, 0xffff0000, v50
	v_lshlrev_b32_e32 v96, 16, v51
	v_and_b32_e32 v97, 0xffff0000, v51
	v_lshlrev_b32_e32 v90, 16, v52
	v_and_b32_e32 v91, 0xffff0000, v52
	v_lshlrev_b32_e32 v92, 16, v53
	v_and_b32_e32 v93, 0xffff0000, v53
	v_lshlrev_b32_e32 v50, 16, v28
	v_and_b32_e32 v51, 0xffff0000, v28
	v_lshlrev_b32_e32 v52, 16, v29
	v_and_b32_e32 v53, 0xffff0000, v29
	v_lshl_add_u64 v[28:29], s[90:91], 0, v[134:135]
	v_mov_b32_e32 v131, v1
	v_lshl_add_u64 v[26:27], v[26:27], 0, s[10:11]
	s_mov_b32 m0, s59
	s_add_i32 s60, s12, 0x1a000
	v_lshlrev_b32_e32 v70, 16, v30
	v_and_b32_e32 v71, 0xffff0000, v30
	v_lshlrev_b32_e32 v72, 16, v31
	v_and_b32_e32 v73, 0xffff0000, v31
	v_lshl_add_u64 v[30:31], s[88:89], 0, v[130:131]
	v_mov_b32_e32 v133, v1
	s_lshl_b32 s8, s8, 13
	s_lshl_b32 s22, s7, 12
	global_load_lds_dwordx4 v[26:27], off
	v_lshl_add_u64 v[26:27], v[28:29], 0, s[10:11]
	s_mov_b32 m0, s60
	s_add_i32 s62, s12, 0x8000
	s_add_i32 s72, s12, 0xa000
	v_lshlrev_b32_e32 v66, 16, v32
	v_and_b32_e32 v67, 0xffff0000, v32
	v_lshlrev_b32_e32 v68, 16, v33
	v_and_b32_e32 v69, 0xffff0000, v33
	v_lshl_add_u64 v[32:33], s[88:89], 0, v[132:133]
	global_load_lds_dwordx4 v[26:27], off
	v_lshl_add_u64 v[26:27], v[30:31], 0, s[10:11]
	s_mov_b32 m0, s62
	s_add_u32 s20, s90, 0xb0080
	global_load_lds_dwordx4 v[26:27], off
	v_lshl_add_u64 v[26:27], v[32:33], 0, s[10:11]
	s_mov_b32 m0, s72
	s_addc_u32 s21, s91, 0
	s_add_i32 s74, s12, 0x1c000
	global_load_lds_dwordx4 v[26:27], off
	v_lshl_add_u64 v[26:27], s[20:21], 0, v[0:1]
	s_mov_b32 m0, s74
	s_add_i32 s19, s12, 0x1e000
	global_load_lds_dwordx4 v[26:27], off
	v_lshl_add_u64 v[26:27], s[20:21], 0, v[134:135]
	s_mov_b32 m0, s19
	v_or_b32_e32 v144, s1, v146
	global_load_lds_dwordx4 v[26:27], off
	s_waitcnt vmcnt(10)
	s_barrier
	v_lshlrev_b32_e32 v145, 6, v144
	v_lshlrev_b32_e32 v149, 4, v136
	s_movk_i32 s1, 0x3c0
	v_lshlrev_b32_e32 v150, 2, v144
	v_and_or_b32 v145, v145, s1, v149
	v_and_b32_e32 v150, 32, v150
	v_bitop3_b32 v145, v145, s8, v150 bitop3:0xde
	s_movk_i32 s8, 0xb00
	v_cmp_eq_u32_e64 s[36:37], 0, v136
	v_lshrrev_b32_e32 v137, 1, v137
	v_mul_lo_u32 v136, v139, s8
	s_mov_b32 s20, 0xb000
	v_or_b32_e32 v147, s0, v147
	v_mad_u64_u32 v[136:137], s[0:1], v137, s20, v[136:137]
	v_or_b32_e32 v136, v136, v138
	v_lshrrev_b32_e32 v139, 1, v141
	v_mul_lo_u32 v138, v143, s8
	v_lshl_or_b32 v149, v146, 6, v149
	v_lshlrev_b32_e32 v146, 2, v146
	v_mad_u64_u32 v[138:139], s[0:1], v139, s20, v[138:139]
	v_and_b32_e32 v146, 32, v146
	s_waitcnt vmcnt(6)
	v_or_b32_e32 v138, v138, v142
	v_bitop3_b32 v146, v149, s22, v146 bitop3:0xde
	v_add_lshl_u32 v136, v136, v140, 1
	v_mov_b32_e32 v137, v1
	s_mov_b64 s[22:23], 0xb0080
	v_add_lshl_u32 v138, v138, v148, 1
	v_mov_b32_e32 v139, v1
	v_lshlrev_b32_e32 v126, 16, v62
	v_and_b32_e32 v127, 0xffff0000, v62
	v_lshlrev_b32_e32 v128, 16, v63
	v_and_b32_e32 v129, 0xffff0000, v63
	v_lshlrev_b32_e32 v122, 16, v64
	v_and_b32_e32 v123, 0xffff0000, v64
	v_lshlrev_b32_e32 v124, 16, v65
	v_and_b32_e32 v125, 0xffff0000, v65
	v_lshlrev_b32_e32 v110, 16, v58
	v_and_b32_e32 v111, 0xffff0000, v58
	v_lshlrev_b32_e32 v112, 16, v59
	v_and_b32_e32 v113, 0xffff0000, v59
	v_lshlrev_b32_e32 v106, 16, v60
	v_and_b32_e32 v107, 0xffff0000, v60
	v_lshlrev_b32_e32 v108, 16, v61
	v_and_b32_e32 v109, 0xffff0000, v61
	v_lshlrev_b32_e32 v102, 16, v46
	v_and_b32_e32 v103, 0xffff0000, v46
	v_lshlrev_b32_e32 v104, 16, v47
	v_and_b32_e32 v105, 0xffff0000, v47
	v_lshlrev_b32_e32 v98, 16, v48
	v_and_b32_e32 v99, 0xffff0000, v48
	v_lshlrev_b32_e32 v100, 16, v49
	v_and_b32_e32 v101, 0xffff0000, v49
	v_lshlrev_b32_e32 v86, 16, v38
	v_and_b32_e32 v87, 0xffff0000, v38
	v_lshlrev_b32_e32 v88, 16, v39
	v_and_b32_e32 v89, 0xffff0000, v39
	v_lshlrev_b32_e32 v82, 16, v40
	v_and_b32_e32 v83, 0xffff0000, v40
	v_lshlrev_b32_e32 v84, 16, v41
	v_and_b32_e32 v85, 0xffff0000, v41
	v_lshlrev_b32_e32 v78, 16, v42
	v_and_b32_e32 v79, 0xffff0000, v42
	v_lshlrev_b32_e32 v80, 16, v43
	v_and_b32_e32 v81, 0xffff0000, v43
	v_lshlrev_b32_e32 v74, 16, v44
	v_and_b32_e32 v75, 0xffff0000, v44
	v_lshlrev_b32_e32 v76, 16, v45
	v_and_b32_e32 v77, 0xffff0000, v45
	v_lshlrev_b32_e32 v62, 16, v34
	v_and_b32_e32 v63, 0xffff0000, v34
	v_lshlrev_b32_e32 v64, 16, v35
	v_and_b32_e32 v65, 0xffff0000, v35
	v_lshlrev_b32_e32 v58, 16, v36
	v_and_b32_e32 v59, 0xffff0000, v36
	v_lshlrev_b32_e32 v60, 16, v37
	v_and_b32_e32 v61, 0xffff0000, v37
	v_lshlrev_b32_e32 v46, 16, v22
	v_and_b32_e32 v47, 0xffff0000, v22
	v_lshlrev_b32_e32 v48, 16, v23
	v_and_b32_e32 v49, 0xffff0000, v23
	v_lshlrev_b32_e32 v42, 16, v24
	v_and_b32_e32 v43, 0xffff0000, v24
	v_lshlrev_b32_e32 v44, 16, v25
	v_and_b32_e32 v45, 0xffff0000, v25
	v_lshlrev_b32_e32 v38, 16, v14
	v_and_b32_e32 v39, 0xffff0000, v14
	v_lshlrev_b32_e32 v40, 16, v15
	v_and_b32_e32 v41, 0xffff0000, v15
	v_lshlrev_b32_e32 v34, 16, v16
	v_and_b32_e32 v35, 0xffff0000, v16
	v_lshlrev_b32_e32 v36, 16, v17
	v_and_b32_e32 v37, 0xffff0000, v17
	v_lshlrev_b32_e32 v30, 16, v18
	v_and_b32_e32 v31, 0xffff0000, v18
	v_lshlrev_b32_e32 v32, 16, v19
	v_and_b32_e32 v33, 0xffff0000, v19
	v_lshlrev_b32_e32 v26, 16, v20
	v_and_b32_e32 v27, 0xffff0000, v20
	v_lshlrev_b32_e32 v28, 16, v21
	v_and_b32_e32 v29, 0xffff0000, v21
	v_lshlrev_b32_e32 v22, 16, v6
	v_and_b32_e32 v23, 0xffff0000, v6
	v_lshlrev_b32_e32 v24, 16, v7
	v_and_b32_e32 v25, 0xffff0000, v7
	v_lshlrev_b32_e32 v18, 16, v8
	v_and_b32_e32 v19, 0xffff0000, v8
	v_lshlrev_b32_e32 v20, 16, v9
	v_and_b32_e32 v21, 0xffff0000, v9
	v_lshlrev_b32_e32 v14, 16, v10
	v_and_b32_e32 v15, 0xffff0000, v10
	v_lshlrev_b32_e32 v16, 16, v11
	v_and_b32_e32 v17, 0xffff0000, v11
	v_lshlrev_b32_e32 v10, 16, v12
	v_and_b32_e32 v11, 0xffff0000, v12
	v_lshlrev_b32_e32 v12, 16, v13
	v_and_b32_e32 v13, 0xffff0000, v13
	v_lshlrev_b32_e32 v6, 16, v2
	v_and_b32_e32 v7, 0xffff0000, v2
	v_lshlrev_b32_e32 v8, 16, v3
	v_and_b32_e32 v9, 0xffff0000, v3
	v_lshlrev_b32_e32 v2, 16, v4
	v_and_b32_e32 v3, 0xffff0000, v4
	v_lshlrev_b32_e32 v4, 16, v5
	v_and_b32_e32 v5, 0xffff0000, v5
	s_mov_b32 s42, 0
	v_lshl_add_u64 v[136:137], v[136:137], 0, s[22:23]
	v_lshl_add_u64 v[138:139], v[138:139], 0, s[22:23]
	s_barrier
	s_branch .LBB0_673
